# stack: full-line f32 partial stores + phase-1 tail (WL loads hoisted, transposes wave rotation) + chunk_prep deferred fragment stores, on top of previous best
# speedup vs baseline: 1.0075x; 1.0047x over previous
; #define LAS __attribute__((address_space(3)))
; DI unsigned f2bf(float f) { unsigned u = __builtin_bit_cast(unsigned, f); return (u + 0x7fffu + ((u >> 16) & 1u)) >> 16; }
; #define P (*args_here())
; DI void p0_transposes(const Ptrs& P, LAS unsigned char* lds, int lo, int hi, int w, int NW, int wave, int lane) {
;     unsigned char* ws = P.ws;
;     LAS float* scr = (LAS float*)(lds + RING_OFF + wave * 16384);
;     for (int it = lo + w; it < hi; it += NW) {
;         int r = it;
;         if (r < 4 * P0_I_GU) {
;             const int which = r / P0_I_GU; r -= which * P0_I_GU; const int nblk = FF / 32, kb = r / nblk, nb = r % nblk;
;             const float* W = which == 0 ? P.in[9] : which == 1 ? P.in[10] : which == 2 ? P.in[32] : P.in[33];
;             bf16* WT = (bf16*)(ws + (which < 2 ? WS_WGUA : WS_WGUB));
;             p0_transpose_item(W, DM, FF, WT, kb, nb, gu_row(32 * nb, which & 1), scr, lane); continue; }
;         r -= 4 * P0_I_GU;
;         if (r < 2 * P0_I_D) { const int which = r / P0_I_D; r -= which * P0_I_D; const int nblk = DM / 32, kb = r / nblk, nb = r % nblk;
;             p0_transpose_item(which ? P.in[34] : P.in[11], FF, DM, (bf16*)(ws + (which ? WS_WDB : WS_WDA)), kb, nb, 32 * nb, scr, lane); continue; }
; DI void p0_small(const Ptrs& P, int gt, int NGT) {
;     ...
;     { bf16* WL = (bf16*)(ws + WS_WL); const float* wl = P.in[20]; const float* al = P.in[22]; const float* gl = P.in[23];
;       for (int i = gt; i < 1536 * 256; i += NGT) { const int n = i >> 8, k = i & 255; float v = 0.f;
;           if (n < 512) { if (k < 64) v = wl[k * 512 + n]; }
;           else if (n < 1024) { if (k >= 64 && k < 128) v = al[(k - 64) * 512 + (n - 512)]; }
;           else { if (k >= 128) v = gl[(k - 128) * 512 + (n - 1024)]; }
;           WL[i] = (bf16)f2bf(v); } }
.Lmy_wl_42:
	s_mov_b64 exec, s[16:17]
	s_add_i32 s0, s33, 0xffffffa8
	s_load_dwordx2 s[4:5], s[2:3], 0x130
	s_lshl_b32 s1, s0, 3
	v_readlane_b32 s6, v254, 9
	s_add_i32 s1, s6, s1
	s_add_i32 s6, s1, 0x1600
	s_cmpk_gt_i32 s6, 0x1b7f
	v_readlane_b32 s7, v254, 10
	s_cbranch_scc1 .LBB0_100
	s_load_dwordx2 s[8:9], s[2:3], 0x58
	v_readlane_b32 s6, v254, 9
	v_lshlrev_b32_e32 v4, 3, v0
	s_lshl_b32 s6, s6, 14
	v_and_b32_e32 v8, 31, v0
	v_lshrrev_b32_e32 v10, 3, v186
	v_and_b32_e32 v16, 56, v4
	s_add_i32 s6, s6, 0
	v_mov_b32_e32 v3, 0
	v_lshlrev_b32_e32 v2, 2, v8
	v_mul_u32_u24_e32 v4, 0x84, v16
	v_lshlrev_b32_e32 v5, 2, v10
	v_lshrrev_b32_e32 v1, 5, v186
	v_add_u32_e32 v9, s6, v2
	v_add3_u32 v11, s6, v4, v5
	s_waitcnt lgkmcnt(0)
	v_lshl_add_u64 v[4:5], s[8:9], 0, v[2:3]
	v_lshlrev_b32_e32 v2, 1, v16
	v_mul_u32_u24_e32 v15, 0x84, v1
	v_lshl_add_u64 v[6:7], s[4:5], 0, v[2:3]
	s_mov_b64 s[8:9], 0xd00000
	v_readlane_b32 s7, v254, 10
	v_lshl_add_u64 v[6:7], v[6:7], 0, s[8:9]
	v_readlane_b32 s8, v254, 11
	v_add_u32_e32 v15, v9, v15
	s_mov_b32 s7, 0
	v_or_b32_e32 v12, 8, v10
	v_or_b32_e32 v13, 16, v10
	v_or_b32_e32 v14, 24, v10
	s_lshl_b32 s10, s1, 1
	s_lshl_b32 s11, s1, 5
	s_add_i32 s12, s8, 0x18bf
	s_add_i32 s98, s1, 0x440
	s_cmp_ge_i32 s98, 0x540
	s_cselect_b32 s99, 0xfffffac0, 0
	s_add_i32 s98, s98, s99
	s_sub_i32 s99, s98, s1
	s_add_i32 s12, s12, s99
	s_lshl_b32 s10, s98, 1
	s_lshl_b32 s11, s98, 5
	s_movk_i32 s13, 0x7fff
	s_mov_b32 s14, 0xffff0000
	s_movk_i32 s15, 0x100
	s_mov_b32 s16, 0x200000
	v_lshlrev_b32_e32 v2, 2, v8
	s_movk_i32 s17, 0x2c00
	v_lshlrev_b32_e32 v8, 1, v16
	v_add_u32_e32 v16, 0x400, v15
	v_add_u32_e32 v17, 0x800, v15
	v_add_u32_e32 v18, 0xc00, v15
	v_add_u32_e32 v19, 0x1000, v15
	v_add_u32_e32 v20, 0x1400, v15
	v_add_u32_e32 v21, 0x1800, v15
	v_add_u32_e32 v22, 0x1c00, v15
	v_mov_b32_e32 v23, 0xaff
	v_readlane_b32 s9, v254, 12
	s_branch .LBB0_96
